# v053 + W_in and FFN2-in GEMM epilogues keep the row-panel rstd values in registers across consecutive units of the same panel (reload + rsqrt only when the panel changes)
# speedup vs baseline: 1.0022x; 1.0022x over previous
;     __device__ bool next(int i, Unit& u) const { if (!b.next(i / 3, u)) return false; u.pz = i % 3; return true; }
; #define PG8_STAGE(bufoff, gbase, voff) do { _Pragma("unroll") for (int _i = 0; _i < 2; ++_i) \
;         __builtin_amdgcn_global_load_lds((const gunsigned*)((const gchar*)(gbase) + (voff)[_i]), (LAS unsigned*)(lds + (bufoff) + ldsw + _i * 8192), 16, 0, 0); } while (0)
; #define PG8_WAIT_V(n) asm volatile("s_waitcnt vmcnt(" #n ")" ::: "memory")
; template <class Epi, class Sched>
; __device__ __forceinline__ void gemm_phase(LAS unsigned char* lds, const int tid, const Gemm g, const Sched& S, const Epi& E) {
;     const int wid = __builtin_amdgcn_readfirstlane(tid >> 6), lane = tid & 63, wr = wid >> 2, wc = wid & 3, fr = lane & 15, fq = lane >> 4;
;     const int K = g.K, nt = K / BK;
;     unsigned voffA[2], voffB[2];
; #pragma unroll
;     for (int i = 0; i < 2; ++i) { int R, C; stage_rc(tid * 16 + i * 8192, R, C); const int Rb = Epi::PERM ? ((R & ~31) + perm32(R & 31)) : R;
;         voffA[i] = (unsigned)(R * K + C) * 2u; voffB[i] = (unsigned)(Rb * K + C) * 2u; }
;     const size_t kstep = (size_t)(BK * 2);
;     const size_t hstep = (size_t)HALF * K * 2;
;     const size_t tstep = 2 * hstep;
;     const unsigned ldsw = (unsigned)wid * 1024u;
;     const int aoff = lds_byte(wr * 64 + fr, fq * 8), boff = lds_byte(wc * 32 + fr, fq * 8);
;     ...
;     Unit cur, nxt; int ui = 0;
;     if (!S.next(0, cur)) return;
;     f32x4 acc[2][2][4][2];
; #pragma unroll
;     for (int a = 0; a < 2; ++a)
; #pragma unroll
;         for (int b = 0; b < 2; ++b)
; #pragma unroll
;             for (int m = 0; m < 4; ++m)
; #pragma unroll
;                 for (int n = 0; n < 2; ++n) acc[a][b][m][n] = (f32x4){0.f, 0.f, 0.f, 0.f};
;     bf16x8 At[4][2], B0[2][2], B1[2][2];
;     const gchar* cA = (const gchar*)g.A + (size_t)cur.pm * tstep + (size_t)cur.pz * g.zA; const gchar* cB = (const gchar*)g.Bt + (size_t)cur.pn * tstep + (size_t)cur.pz * g.zB;
;     PG8_STAGE(PG8_SB(0, 0), cB, voffB); PG8_STAGE(PG8_SB(0, 1), cB + hstep, voffB); PG8_STAGE(PG8_SA(0, 0), cA, voffA); PG8_STAGE(PG8_SA(0, 1), cA + hstep, voffA);
;     if (wr == 1) PG8_BAR;
;     PG8_WAIT_V(2); PG8_BAR;
;     PG8_STAGE(PG8_SB(1, 0), cB + kstep, voffB); PG8_STAGE(PG8_SA(1, 0), cA + kstep, voffA); PG8_STAGE(PG8_SB(1, 1), cB + hstep + kstep, voffB);
;     PG8_WAIT_V(6); PG8_BAR;
.LBB0_363:
	v_mov_b32_e32 v242, -1
	v_lshrrev_b32_e32 v17, 1, v240
	v_and_b32_e32 v17, 24, v17
	v_and_b32_e32 v16, 15, v240
	v_lshlrev_b32_e32 v18, 1, v17
	v_lshl_or_b32 v143, s7, 6, v16
	v_lshl_or_b32 v16, v16, 6, v18
	v_lshlrev_b32_e32 v18, 2, v240
	s_sext_i32_i16 s1, s2
	s_lshl_b32 s2, s7, 13
	v_and_b32_e32 v18, 32, v18
	v_bitop3_b32 v19, v16, s2, v18 bitop3:0xde
	s_lshl_b32 s2, s6, 5
	s_and_b32 s2, s2, 0x60
	s_add_i32 m0, s73, 0x18000
	v_lshl_add_u64 v[8:9], v[8:9], 0, s[68:69]
	s_lshl_b32 s6, s2, 7
	s_waitcnt vmcnt(2)
	s_barrier
	global_load_lds_dwordx4 v[8:9], off
	v_lshl_add_u64 v[6:7], v[6:7], 0, s[68:69]
	s_add_i32 m0, s73, 0x1a000
	s_add_i32 s93, s73, 0x8000
	s_add_i32 s44, s73, 0xa000
	v_bitop3_b32 v145, s6, v16, v18 bitop3:0xf6
	global_load_lds_dwordx4 v[6:7], off
	v_lshl_add_u64 v[2:3], v[2:3], 0, s[68:69]
	s_mov_b32 m0, s93
	s_add_u32 s6, s16, 0x40080
	global_load_lds_dwordx4 v[2:3], off
	v_lshl_add_u64 v[2:3], v[4:5], 0, s[68:69]
	s_mov_b32 m0, s44
	s_addc_u32 s7, s17, 0
	global_load_lds_dwordx4 v[2:3], off
	s_add_i32 m0, s73, 0x1c000
	v_lshl_add_u64 v[2:3], s[6:7], 0, v[0:1]
	global_load_lds_dwordx4 v[2:3], off
	v_lshl_add_u64 v[2:3], s[6:7], 0, v[130:131]
	s_add_i32 m0, s73, 0x1e000
	s_cmpk_lt_u32 s3, 0x100
	global_load_lds_dwordx4 v[2:3], off
	v_lshlrev_b32_e32 v2, 14, v10
	v_and_b32_e32 v2, 0xffff8000, v2
	v_lshl_add_u32 v2, v11, 11, v2
	v_and_b32_e32 v3, 1, v10
	v_lshl_or_b32 v2, v3, 6, v2
	v_lshl_add_u32 v136, v12, 1, v2
	v_lshlrev_b32_e32 v2, 14, v14
	v_and_b32_e32 v2, 0xffff8000, v2
	s_waitcnt vmcnt(6)
	v_lshl_add_u32 v2, v13, 11, v2
	v_and_b32_e32 v3, 1, v14
	v_lshl_or_b32 v2, v3, 6, v2
	s_cselect_b64 s[6:7], -1, 0
	v_or_b32_e32 v151, s2, v17
	v_mov_b32_e32 v137, v1
	v_lshl_add_u32 v138, v15, 1, v2
	v_mov_b32_e32 v139, v1
	s_mov_b32 s45, 0
	v_add_u32_e32 v155, 0, v19
	s_barrier
	s_branch .LBB0_366

; __device__ __forceinline__ unsigned pk2(float lo, float hi) { f32x2 v = {lo, hi}; bf16x2_t b = __builtin_convertvector(v, bf16x2_t); return __builtin_bit_cast(unsigned, b); }
; __device__ __forceinline__ float sigmoidf_(float x) { return __builtin_amdgcn_rcpf(1.0f + __builtin_amdgcn_exp2f(-x * LOG2E)); }
;     __device__ __forceinline__ void operator()(const f32x4 (&acc)[2][2][4][2], const Unit& u, int wr, int wc, int fr, int fq, LAS unsigned char* lds, int tid) const {
;     ...
;         { f32x4 pv_[2][4];
; #pragma unroll
;           for (int ai = 0; ai < 2; ++ai)
; #pragma unroll
;               for (int m = 0; m < 4; ++m) pv_[ai][m] = *(const gf32x4*)(ssq + (size_t)(row0 + ai * HALF + m * 16) * 4);
;           asm volatile("" ::: "memory");
; #pragma unroll
;           for (int ai = 0; ai < 2; ++ai)
; #pragma unroll
;               for (int m = 0; m < 4; ++m) { const f32x4 p = pv_[ai][m]; rsv[ai][m] = __builtin_amdgcn_rsqf(((p.x + p.y) + (p.z + p.w)) * (1.0f / DM) + EPS); } }
; #pragma unroll
;         for (int ai = 0; ai < 2; ++ai)
; #pragma unroll
;             for (int m = 0; m < 4; ++m) { const size_t row = (size_t)(row0 + ai * HALF + m * 16); const float rs = rsv[ai][m]; gbf16* rowp = O + row * FF + col0;
;                 float h[8];
; #pragma unroll
;                 for (int n = 0; n < 2; ++n)
; #pragma unroll
;                     for (int e = 0; e < 4; ++e) { const float g = acc[ai][0][m][n][e] * rs, uu = acc[ai][1][m][n][e] * rs; h[n * 4 + e] = g * sigmoidf_(g) * uu; }
;                 u32x4 w; w.x = pk2(h[0], h[1]); w.y = pk2(h[2], h[3]); w.z = pk2(h[4], h[5]); w.w = pk2(h[6], h[7]);
;                 *(gu32x4*)rowp = w; }
.LBB0_372:
	v_lshl_add_u32 v172, s0, 8, v143
	v_or_b32_e32 v168, 16, v172
	v_or_b32_e32 v164, 32, v172
	v_or_b32_e32 v160, 48, v172
	v_add_u32_e32 v156, 0x80, v172
	v_add_u32_e32 v152, 0x90, v172
	v_add_u32_e32 v146, 0xa0, v172
	v_add_u32_e32 v140, 0xb0, v172
	v_readfirstlane_b32 vcc_lo, v242
	s_cmp_eq_u32 s0, vcc_lo
	s_cbranch_scc1 .Lk8_rs_hit
	v_mov_b32_e32 v242, s0
	v_ashrrev_i32_e32 v149, 31, v172
	v_mov_b32_e32 v148, v172
	v_lshl_add_u64 v[148:149], v[148:149], 4, s[70:71]
	global_load_dwordx4 v[174:177], v[148:149], off
	v_ashrrev_i32_e32 v149, 31, v168
	v_mov_b32_e32 v148, v168
	v_lshl_add_u64 v[148:149], v[148:149], 4, s[70:71]
	global_load_dwordx4 v[178:181], v[148:149], off
	v_ashrrev_i32_e32 v149, 31, v164
	v_mov_b32_e32 v148, v164
	v_lshl_add_u64 v[148:149], v[148:149], 4, s[70:71]
	global_load_dwordx4 v[182:185], v[148:149], off
	v_ashrrev_i32_e32 v149, 31, v160
	v_mov_b32_e32 v148, v160
	v_lshl_add_u64 v[148:149], v[148:149], 4, s[70:71]
	global_load_dwordx4 v[186:189], v[148:149], off
	v_ashrrev_i32_e32 v149, 31, v156
	v_mov_b32_e32 v148, v156
	v_lshl_add_u64 v[148:149], v[148:149], 4, s[70:71]
	global_load_dwordx4 v[190:193], v[148:149], off
	v_ashrrev_i32_e32 v149, 31, v152
	v_mov_b32_e32 v148, v152
	v_lshl_add_u64 v[148:149], v[148:149], 4, s[70:71]
	global_load_dwordx4 v[204:207], v[148:149], off
	v_ashrrev_i32_e32 v149, 31, v146
	v_mov_b32_e32 v148, v146
	v_lshl_add_u64 v[148:149], v[148:149], 4, s[70:71]
	global_load_dwordx4 v[208:211], v[148:149], off
	v_ashrrev_i32_e32 v149, 31, v140
	v_mov_b32_e32 v148, v140
	v_lshl_add_u64 v[148:149], v[148:149], 4, s[70:71]
	global_load_dwordx4 v[212:215], v[148:149], off
	s_waitcnt vmcnt(0)
	v_add_f32_e32 v174, v174, v175
	v_add_f32_e32 v176, v176, v177
	v_add_f32_e32 v174, v174, v176
	v_fmamk_f32 v174, v174, 0x3a800000, v235
	v_rsq_f32_e32 v226, v174
	v_add_f32_e32 v178, v178, v179
	v_add_f32_e32 v180, v180, v181
	v_add_f32_e32 v178, v178, v180
	v_fmamk_f32 v178, v178, 0x3a800000, v235
	v_rsq_f32_e32 v236, v178
	v_add_f32_e32 v182, v182, v183
	v_add_f32_e32 v184, v184, v185
	v_add_f32_e32 v182, v182, v184
	v_fmamk_f32 v182, v182, 0x3a800000, v235
	v_rsq_f32_e32 v237, v182
	v_add_f32_e32 v186, v186, v187
	v_add_f32_e32 v188, v188, v189
	v_add_f32_e32 v186, v186, v188
	v_fmamk_f32 v186, v186, 0x3a800000, v235
	v_rsq_f32_e32 v244, v186
	v_add_f32_e32 v190, v190, v191
	v_add_f32_e32 v192, v192, v193
	v_add_f32_e32 v190, v190, v192
	v_fmamk_f32 v190, v190, 0x3a800000, v235
	v_rsq_f32_e32 v245, v190
	v_add_f32_e32 v204, v204, v205
	v_add_f32_e32 v206, v206, v207
	v_add_f32_e32 v204, v204, v206
	v_fmamk_f32 v204, v204, 0x3a800000, v235
	v_rsq_f32_e32 v246, v204
	v_add_f32_e32 v208, v208, v209
	v_add_f32_e32 v210, v210, v211
	v_add_f32_e32 v208, v208, v210
	v_fmamk_f32 v208, v208, 0x3a800000, v235
	v_rsq_f32_e32 v247, v208
	v_add_f32_e32 v212, v212, v213
	v_add_f32_e32 v214, v214, v215
	v_add_f32_e32 v212, v212, v214
	v_fmamk_f32 v212, v212, 0x3a800000, v235
	v_rsq_f32_e32 v248, v212
.Lk8_rs_hit:
	s_andn2_b64 vcc, exec, s[2:3]
	v_lshl_or_b32 v174, s1, 7, v151
	v_mov_b32_e32 v170, v226
	v_mov_b32_e32 v166, v236
	v_mov_b32_e32 v162, v237
	v_mov_b32_e32 v158, v244
	v_mov_b32_e32 v154, v245
	v_mov_b32_e32 v150, v246
	v_mov_b32_e32 v144, v247
	v_mov_b32_e32 v142, v248
	v_pk_mul_f32 v[126:127], v[126:127], v[170:171] op_sel_hi:[1,0]
	v_mul_f32_e32 v141, 0xbfb8aa3b, v126
	v_exp_f32_e32 v141, v141
	v_pk_mul_f32 v[122:123], v[122:123], v[170:171] op_sel_hi:[1,0]
	v_pk_mul_f32 v[124:125], v[124:125], v[170:171] op_sel_hi:[1,0]
	v_pk_mul_f32 v[118:119], v[118:119], v[170:171] op_sel_hi:[1,0]
	v_add_f32_e32 v141, 1.0, v141
	v_rcp_f32_e32 v176, v141
	v_mul_f32_e32 v141, 0xbfb8aa3b, v127
	v_exp_f32_e32 v141, v141
	v_pk_mul_f32 v[114:115], v[114:115], v[170:171] op_sel_hi:[1,0]
	v_ashrrev_i32_e32 v175, 31, v174
	v_mov_b64_e32 v[148:149], s[88:89]
	v_add_f32_e32 v141, 1.0, v141
	v_rcp_f32_e32 v177, v141
	v_pk_mul_f32 v[116:117], v[116:117], v[170:171] op_sel_hi:[1,0]
	v_mad_i64_i32 v[172:173], s[0:1], v172, s79, v[148:149]
	v_pk_mul_f32 v[126:127], v[126:127], v[176:177]
	v_pk_mul_f32 v[110:111], v[110:111], v[166:167] op_sel_hi:[1,0]
	v_pk_mul_f32 v[122:123], v[122:123], v[126:127]
	v_pk_mul_f32 v[126:127], v[128:129], v[170:171] op_sel_hi:[1,0]
	v_pk_mul_f32 v[106:107], v[106:107], v[166:167] op_sel_hi:[1,0]
	v_mul_f32_e32 v128, 0xbfb8aa3b, v126
	v_mul_f32_e32 v129, 0xbfb8aa3b, v127
	v_exp_f32_e32 v128, v128
	v_exp_f32_e32 v129, v129
	v_pk_mul_f32 v[108:109], v[108:109], v[166:167] op_sel_hi:[1,0]
	v_pk_mul_f32 v[102:103], v[102:103], v[166:167] op_sel_hi:[1,0]
	v_add_f32_e32 v128, 1.0, v128
	v_add_f32_e32 v129, 1.0, v129
	v_rcp_f32_e32 v128, v128
	v_rcp_f32_e32 v129, v129
	v_pk_mul_f32 v[98:99], v[98:99], v[166:167] op_sel_hi:[1,0]
	v_pk_mul_f32 v[100:101], v[100:101], v[166:167] op_sel_hi:[1,0]
	v_pk_mul_f32 v[94:95], v[94:95], v[162:163] op_sel_hi:[1,0]
	v_pk_mul_f32 v[126:127], v[126:127], v[128:129]
	v_pk_mul_f32 v[90:91], v[90:91], v[162:163] op_sel_hi:[1,0]
	v_pk_mul_f32 v[124:125], v[124:125], v[126:127]
	v_mul_f32_e32 v126, 0xbfb8aa3b, v118
	v_mul_f32_e32 v127, 0xbfb8aa3b, v119
	v_exp_f32_e32 v126, v126
	v_exp_f32_e32 v127, v127
	v_pk_mul_f32 v[92:93], v[92:93], v[162:163] op_sel_hi:[1,0]
	v_pk_mul_f32 v[86:87], v[86:87], v[162:163] op_sel_hi:[1,0]
	v_add_f32_e32 v126, 1.0, v126
	v_add_f32_e32 v127, 1.0, v127
	v_rcp_f32_e32 v126, v126
	v_rcp_f32_e32 v127, v127
	v_pk_mul_f32 v[82:83], v[82:83], v[162:163] op_sel_hi:[1,0]
	v_pk_mul_f32 v[84:85], v[84:85], v[162:163] op_sel_hi:[1,0]
	v_pk_mul_f32 v[78:79], v[78:79], v[158:159] op_sel_hi:[1,0]
	v_pk_mul_f32 v[118:119], v[118:119], v[126:127]
; __device__ __forceinline__ unsigned pk2(float lo, float hi) { f32x2 v = {lo, hi}; bf16x2_t b = __builtin_convertvector(v, bf16x2_t); return __builtin_bit_cast(unsigned, b); }
; __device__ __forceinline__ float sigmoidf_(float x) { return __builtin_amdgcn_rcpf(1.0f + __builtin_amdgcn_exp2f(-x * LOG2E)); }
;     __device__ __forceinline__ void operator()(const f32x4 (&acc)[2][2][4][2], const Unit& u, int wr, int wc, int fr, int fq, LAS unsigned char* lds, int tid) const {
;     ...
;         for (int ai = 0; ai < 2; ++ai)
; #pragma unroll
;             for (int m = 0; m < 4; ++m) { const size_t row = (size_t)(row0 + ai * HALF + m * 16); const float rs = rsv[ai][m]; gbf16* rowp = O + row * FF + col0;
;                 float h[8];
; #pragma unroll
;                 for (int n = 0; n < 2; ++n)
; #pragma unroll
;                     for (int e = 0; e < 4; ++e) { const float g = acc[ai][0][m][n][e] * rs, uu = acc[ai][1][m][n][e] * rs; h[n * 4 + e] = g * sigmoidf_(g) * uu; }
;                 u32x4 w; w.x = pk2(h[0], h[1]); w.y = pk2(h[2], h[3]); w.z = pk2(h[4], h[5]); w.w = pk2(h[6], h[7]);
;                 *(gu32x4*)rowp = w; }
	v_pk_mul_f32 v[74:75], v[74:75], v[158:159] op_sel_hi:[1,0]
	v_pk_mul_f32 v[118:119], v[114:115], v[118:119]
	v_pk_mul_f32 v[114:115], v[120:121], v[170:171] op_sel_hi:[1,0]
	v_cvt_pk_bf16_f32 v118, v118, v119
	v_mul_f32_e32 v120, 0xbfb8aa3b, v114
	v_mul_f32_e32 v121, 0xbfb8aa3b, v115
	v_exp_f32_e32 v120, v120
	v_exp_f32_e32 v121, v121
	v_pk_mul_f32 v[76:77], v[76:77], v[158:159] op_sel_hi:[1,0]
	v_pk_mul_f32 v[70:71], v[70:71], v[158:159] op_sel_hi:[1,0]
	v_add_f32_e32 v120, 1.0, v120
	v_add_f32_e32 v121, 1.0, v121
	v_rcp_f32_e32 v120, v120
	v_rcp_f32_e32 v121, v121
	v_pk_mul_f32 v[66:67], v[66:67], v[158:159] op_sel_hi:[1,0]
	v_pk_mul_f32 v[68:69], v[68:69], v[158:159] op_sel_hi:[1,0]
	v_pk_mul_f32 v[62:63], v[62:63], v[154:155] op_sel_hi:[1,0]
	v_pk_mul_f32 v[114:115], v[114:115], v[120:121]
	v_pk_mul_f32 v[58:59], v[58:59], v[154:155] op_sel_hi:[1,0]
	v_pk_mul_f32 v[120:121], v[116:117], v[114:115]
	v_lshlrev_b64 v[114:115], 1, v[174:175]
	v_lshl_add_u64 v[126:127], v[172:173], 0, v[114:115]
	v_cvt_pk_bf16_f32 v116, v122, v123
	v_cvt_pk_bf16_f32 v117, v124, v125
	v_cvt_pk_bf16_f32 v119, v120, v121
	global_store_dwordx4 v[126:127], v[116:119], off
	v_pk_mul_f32 v[60:61], v[60:61], v[154:155] op_sel_hi:[1,0]
	v_pk_mul_f32 v[54:55], v[54:55], v[154:155] op_sel_hi:[1,0]
	v_mul_f32_e32 v118, 0xbfb8aa3b, v110
	v_mul_f32_e32 v119, 0xbfb8aa3b, v111
	v_exp_f32_e32 v118, v118
	v_exp_f32_e32 v119, v119
	v_mad_i64_i32 v[116:117], s[0:1], v168, s79, v[148:149]
	v_add_f32_e32 v118, 1.0, v118
	v_add_f32_e32 v119, 1.0, v119
	v_rcp_f32_e32 v118, v118
	v_rcp_f32_e32 v119, v119
	v_pk_mul_f32 v[50:51], v[50:51], v[154:155] op_sel_hi:[1,0]
	v_pk_mul_f32 v[52:53], v[52:53], v[154:155] op_sel_hi:[1,0]
	v_pk_mul_f32 v[46:47], v[46:47], v[150:151] op_sel_hi:[1,0]
	v_pk_mul_f32 v[110:111], v[110:111], v[118:119]
	v_pk_mul_f32 v[42:43], v[42:43], v[150:151] op_sel_hi:[1,0]
	v_pk_mul_f32 v[106:107], v[106:107], v[110:111]
	v_pk_mul_f32 v[110:111], v[112:113], v[166:167] op_sel_hi:[1,0]
	v_pk_mul_f32 v[44:45], v[44:45], v[150:151] op_sel_hi:[1,0]
	v_mul_f32_e32 v112, 0xbfb8aa3b, v110
	v_mul_f32_e32 v113, 0xbfb8aa3b, v111
	v_exp_f32_e32 v112, v112
	v_exp_f32_e32 v113, v113
	v_pk_mul_f32 v[38:39], v[38:39], v[150:151] op_sel_hi:[1,0]
	v_pk_mul_f32 v[34:35], v[34:35], v[150:151] op_sel_hi:[1,0]
	v_add_f32_e32 v112, 1.0, v112
	v_add_f32_e32 v113, 1.0, v113
	v_rcp_f32_e32 v112, v112
	v_rcp_f32_e32 v113, v113
	v_pk_mul_f32 v[36:37], v[36:37], v[150:151] op_sel_hi:[1,0]
	v_pk_mul_f32 v[30:31], v[30:31], v[144:145] op_sel_hi:[1,0]
	v_pk_mul_f32 v[26:27], v[26:27], v[144:145] op_sel_hi:[1,0]
	v_pk_mul_f32 v[110:111], v[110:111], v[112:113]
	v_pk_mul_f32 v[28:29], v[28:29], v[144:145] op_sel_hi:[1,0]
	v_pk_mul_f32 v[108:109], v[108:109], v[110:111]
	v_mul_f32_e32 v110, 0xbfb8aa3b, v102
	v_mul_f32_e32 v111, 0xbfb8aa3b, v103
	v_exp_f32_e32 v110, v110
	v_exp_f32_e32 v111, v111
	v_pk_mul_f32 v[22:23], v[22:23], v[144:145] op_sel_hi:[1,0]
	v_pk_mul_f32 v[18:19], v[18:19], v[144:145] op_sel_hi:[1,0]
	v_add_f32_e32 v110, 1.0, v110
	v_add_f32_e32 v111, 1.0, v111
	v_rcp_f32_e32 v110, v110
	v_rcp_f32_e32 v111, v111
	v_pk_mul_f32 v[20:21], v[20:21], v[144:145] op_sel_hi:[1,0]
	v_pk_mul_f32 v[14:15], v[14:15], v[142:143] op_sel_hi:[1,0]
	v_pk_mul_f32 v[10:11], v[10:11], v[142:143] op_sel_hi:[1,0]
	v_pk_mul_f32 v[102:103], v[102:103], v[110:111]
	v_lshl_add_u64 v[110:111], v[116:117], 0, v[114:115]
	v_pk_mul_f32 v[102:103], v[98:99], v[102:103]
	v_pk_mul_f32 v[98:99], v[104:105], v[166:167] op_sel_hi:[1,0]
	v_pk_mul_f32 v[12:13], v[12:13], v[142:143] op_sel_hi:[1,0]
	v_mul_f32_e32 v104, 0xbfb8aa3b, v98
	v_mul_f32_e32 v105, 0xbfb8aa3b, v99
	v_exp_f32_e32 v104, v104
	v_exp_f32_e32 v105, v105
	v_pk_mul_f32 v[6:7], v[6:7], v[142:143] op_sel_hi:[1,0]
	v_pk_mul_f32 v[2:3], v[2:3], v[142:143] op_sel_hi:[1,0]
	v_add_f32_e32 v104, 1.0, v104
	v_add_f32_e32 v105, 1.0, v105
	v_rcp_f32_e32 v104, v104
	v_rcp_f32_e32 v105, v105
	v_pk_mul_f32 v[4:5], v[4:5], v[142:143] op_sel_hi:[1,0]
	v_pk_mul_f32 v[98:99], v[98:99], v[104:105]
	s_nop 0
	v_pk_mul_f32 v[104:105], v[100:101], v[98:99]
	v_cvt_pk_bf16_f32 v98, v106, v107
	v_cvt_pk_bf16_f32 v99, v108, v109
	v_cvt_pk_bf16_f32 v100, v102, v103
	v_cvt_pk_bf16_f32 v101, v104, v105
	global_store_dwordx4 v[110:111], v[98:101], off
	s_nop 1
	v_mul_f32_e32 v100, 0xbfb8aa3b, v94
	v_mul_f32_e32 v101, 0xbfb8aa3b, v95
	v_exp_f32_e32 v100, v100
	v_exp_f32_e32 v101, v101
	v_mad_i64_i32 v[98:99], s[0:1], v164, s79, v[148:149]
	v_add_f32_e32 v100, 1.0, v100
	v_add_f32_e32 v101, 1.0, v101
	v_rcp_f32_e32 v100, v100
	v_rcp_f32_e32 v101, v101
	s_nop 0
	v_pk_mul_f32 v[94:95], v[94:95], v[100:101]
	s_nop 0
	v_pk_mul_f32 v[90:91], v[90:91], v[94:95]
	v_pk_mul_f32 v[94:95], v[96:97], v[162:163] op_sel_hi:[1,0]
	s_nop 0
	v_mul_f32_e32 v96, 0xbfb8aa3b, v94
	v_mul_f32_e32 v97, 0xbfb8aa3b, v95
	v_exp_f32_e32 v96, v96
	v_exp_f32_e32 v97, v97
	v_add_f32_e32 v96, 1.0, v96
	v_add_f32_e32 v97, 1.0, v97
	v_rcp_f32_e32 v96, v96
	v_rcp_f32_e32 v97, v97
	s_nop 0
	v_pk_mul_f32 v[94:95], v[94:95], v[96:97]
	s_nop 0
	v_pk_mul_f32 v[92:93], v[92:93], v[94:95]
	v_mul_f32_e32 v94, 0xbfb8aa3b, v86
	v_mul_f32_e32 v95, 0xbfb8aa3b, v87
	v_exp_f32_e32 v94, v94
	v_exp_f32_e32 v95, v95
	v_add_f32_e32 v94, 1.0, v94
	v_add_f32_e32 v95, 1.0, v95
	v_rcp_f32_e32 v94, v94
	v_rcp_f32_e32 v95, v95
	s_nop 0
	v_pk_mul_f32 v[86:87], v[86:87], v[94:95]
	s_nop 0
	v_pk_mul_f32 v[86:87], v[82:83], v[86:87]
	v_pk_mul_f32 v[82:83], v[88:89], v[162:163] op_sel_hi:[1,0]
	v_lshl_add_u64 v[94:95], v[98:99], 0, v[114:115]
	v_mul_f32_e32 v88, 0xbfb8aa3b, v82
	v_mul_f32_e32 v89, 0xbfb8aa3b, v83
	v_exp_f32_e32 v88, v88
; __device__ __forceinline__ unsigned pk2(float lo, float hi) { f32x2 v = {lo, hi}; bf16x2_t b = __builtin_convertvector(v, bf16x2_t); return __builtin_bit_cast(unsigned, b); }
; __device__ __forceinline__ float sigmoidf_(float x) { return __builtin_amdgcn_rcpf(1.0f + __builtin_amdgcn_exp2f(-x * LOG2E)); }
;     __device__ __forceinline__ void operator()(const f32x4 (&acc)[2][2][4][2], const Unit& u, int wr, int wc, int fr, int fq, LAS unsigned char* lds, int tid) const {
;     ...
;         for (int ai = 0; ai < 2; ++ai)
; #pragma unroll
;             for (int m = 0; m < 4; ++m) { const size_t row = (size_t)(row0 + ai * HALF + m * 16); const float rs = rsv[ai][m]; gbf16* rowp = O + row * FF + col0;
;                 float h[8];
; #pragma unroll
;                 for (int n = 0; n < 2; ++n)
; #pragma unroll
;                     for (int e = 0; e < 4; ++e) { const float g = acc[ai][0][m][n][e] * rs, uu = acc[ai][1][m][n][e] * rs; h[n * 4 + e] = g * sigmoidf_(g) * uu; }
;                 u32x4 w; w.x = pk2(h[0], h[1]); w.y = pk2(h[2], h[3]); w.z = pk2(h[4], h[5]); w.w = pk2(h[6], h[7]);
;                 *(gu32x4*)rowp = w; }
	v_exp_f32_e32 v89, v89
	v_add_f32_e32 v88, 1.0, v88
	v_add_f32_e32 v89, 1.0, v89
	v_rcp_f32_e32 v88, v88
	v_rcp_f32_e32 v89, v89
	s_nop 0
	v_pk_mul_f32 v[82:83], v[82:83], v[88:89]
	s_nop 0
	v_pk_mul_f32 v[88:89], v[84:85], v[82:83]
	v_cvt_pk_bf16_f32 v82, v90, v91
	v_cvt_pk_bf16_f32 v83, v92, v93
	v_cvt_pk_bf16_f32 v84, v86, v87
	v_cvt_pk_bf16_f32 v85, v88, v89
	global_store_dwordx4 v[94:95], v[82:85], off
	s_nop 1
	v_mul_f32_e32 v84, 0xbfb8aa3b, v78
	v_mul_f32_e32 v85, 0xbfb8aa3b, v79
	v_exp_f32_e32 v84, v84
	v_exp_f32_e32 v85, v85
	v_mad_i64_i32 v[82:83], s[0:1], v160, s79, v[148:149]
	v_add_f32_e32 v84, 1.0, v84
	v_add_f32_e32 v85, 1.0, v85
	v_rcp_f32_e32 v84, v84
	v_rcp_f32_e32 v85, v85
	s_nop 0
	v_pk_mul_f32 v[78:79], v[78:79], v[84:85]
	s_nop 0
	v_pk_mul_f32 v[74:75], v[74:75], v[78:79]
	v_pk_mul_f32 v[78:79], v[80:81], v[158:159] op_sel_hi:[1,0]
	s_nop 0
	v_mul_f32_e32 v80, 0xbfb8aa3b, v78
	v_mul_f32_e32 v81, 0xbfb8aa3b, v79
	v_exp_f32_e32 v80, v80
	v_exp_f32_e32 v81, v81
	v_add_f32_e32 v80, 1.0, v80
	v_add_f32_e32 v81, 1.0, v81
	v_rcp_f32_e32 v80, v80
	v_rcp_f32_e32 v81, v81
	s_nop 0
	v_pk_mul_f32 v[78:79], v[78:79], v[80:81]
	s_nop 0
	v_pk_mul_f32 v[76:77], v[76:77], v[78:79]
	v_mul_f32_e32 v78, 0xbfb8aa3b, v70
	v_mul_f32_e32 v79, 0xbfb8aa3b, v71
	v_exp_f32_e32 v78, v78
	v_exp_f32_e32 v79, v79
	v_add_f32_e32 v78, 1.0, v78
	v_add_f32_e32 v79, 1.0, v79
	v_rcp_f32_e32 v78, v78
	v_rcp_f32_e32 v79, v79
	s_nop 0
	v_pk_mul_f32 v[70:71], v[70:71], v[78:79]
	s_nop 0
	v_pk_mul_f32 v[70:71], v[66:67], v[70:71]
	v_pk_mul_f32 v[66:67], v[72:73], v[158:159] op_sel_hi:[1,0]
	v_lshl_add_u64 v[78:79], v[82:83], 0, v[114:115]
	v_mul_f32_e32 v72, 0xbfb8aa3b, v66
	v_mul_f32_e32 v73, 0xbfb8aa3b, v67
	v_exp_f32_e32 v72, v72
	v_exp_f32_e32 v73, v73
	v_add_f32_e32 v72, 1.0, v72
	v_add_f32_e32 v73, 1.0, v73
	v_rcp_f32_e32 v72, v72
	v_rcp_f32_e32 v73, v73
	s_nop 0
	v_pk_mul_f32 v[66:67], v[66:67], v[72:73]
	s_nop 0
	v_pk_mul_f32 v[72:73], v[68:69], v[66:67]
	v_cvt_pk_bf16_f32 v66, v74, v75
	v_cvt_pk_bf16_f32 v67, v76, v77
	v_cvt_pk_bf16_f32 v68, v70, v71
	v_cvt_pk_bf16_f32 v69, v72, v73
	global_store_dwordx4 v[78:79], v[66:69], off
	s_nop 1
	v_mul_f32_e32 v68, 0xbfb8aa3b, v62
	v_mul_f32_e32 v69, 0xbfb8aa3b, v63
	v_exp_f32_e32 v68, v68
	v_exp_f32_e32 v69, v69
	v_mad_i64_i32 v[66:67], s[0:1], v156, s79, v[148:149]
	v_add_f32_e32 v68, 1.0, v68
	v_add_f32_e32 v69, 1.0, v69
	v_rcp_f32_e32 v68, v68
	v_rcp_f32_e32 v69, v69
	s_nop 0
	v_pk_mul_f32 v[62:63], v[62:63], v[68:69]
	s_nop 0
	v_pk_mul_f32 v[58:59], v[58:59], v[62:63]
	v_pk_mul_f32 v[62:63], v[64:65], v[154:155] op_sel_hi:[1,0]
	s_nop 0
	v_mul_f32_e32 v64, 0xbfb8aa3b, v62
	v_mul_f32_e32 v65, 0xbfb8aa3b, v63
	v_exp_f32_e32 v64, v64
	v_exp_f32_e32 v65, v65
	v_add_f32_e32 v64, 1.0, v64
	v_add_f32_e32 v65, 1.0, v65
	v_rcp_f32_e32 v64, v64
	v_rcp_f32_e32 v65, v65
	s_nop 0
	v_pk_mul_f32 v[62:63], v[62:63], v[64:65]
	s_nop 0
	v_pk_mul_f32 v[60:61], v[60:61], v[62:63]
	v_mul_f32_e32 v62, 0xbfb8aa3b, v54
	v_mul_f32_e32 v63, 0xbfb8aa3b, v55
	v_exp_f32_e32 v62, v62
	v_exp_f32_e32 v63, v63
	v_add_f32_e32 v62, 1.0, v62
	v_add_f32_e32 v63, 1.0, v63
	v_rcp_f32_e32 v62, v62
	v_rcp_f32_e32 v63, v63
	s_nop 0
	v_pk_mul_f32 v[54:55], v[54:55], v[62:63]
	s_nop 0
	v_pk_mul_f32 v[54:55], v[50:51], v[54:55]
	v_pk_mul_f32 v[50:51], v[56:57], v[154:155] op_sel_hi:[1,0]
	v_lshl_add_u64 v[62:63], v[66:67], 0, v[114:115]
	v_mul_f32_e32 v56, 0xbfb8aa3b, v50
	v_mul_f32_e32 v57, 0xbfb8aa3b, v51
	v_exp_f32_e32 v56, v56
	v_exp_f32_e32 v57, v57
	v_add_f32_e32 v56, 1.0, v56
	v_add_f32_e32 v57, 1.0, v57
	v_rcp_f32_e32 v56, v56
	v_rcp_f32_e32 v57, v57
	s_nop 0
	v_pk_mul_f32 v[50:51], v[50:51], v[56:57]
	s_nop 0
	v_pk_mul_f32 v[56:57], v[52:53], v[50:51]
	v_cvt_pk_bf16_f32 v50, v58, v59
	v_cvt_pk_bf16_f32 v51, v60, v61
	v_cvt_pk_bf16_f32 v52, v54, v55
	v_cvt_pk_bf16_f32 v53, v56, v57
	global_store_dwordx4 v[62:63], v[50:53], off
	s_nop 1
	v_mul_f32_e32 v52, 0xbfb8aa3b, v46
	v_mul_f32_e32 v53, 0xbfb8aa3b, v47
	v_exp_f32_e32 v52, v52
	v_exp_f32_e32 v53, v53
	v_mad_i64_i32 v[50:51], s[0:1], v152, s79, v[148:149]
	v_add_f32_e32 v52, 1.0, v52
	v_add_f32_e32 v53, 1.0, v53
	v_rcp_f32_e32 v52, v52
	v_rcp_f32_e32 v53, v53
	s_nop 0
	v_pk_mul_f32 v[46:47], v[46:47], v[52:53]
	s_nop 0
	v_pk_mul_f32 v[42:43], v[42:43], v[46:47]
	v_pk_mul_f32 v[46:47], v[48:49], v[150:151] op_sel_hi:[1,0]
	s_nop 0
	v_mul_f32_e32 v48, 0xbfb8aa3b, v46
	v_mul_f32_e32 v49, 0xbfb8aa3b, v47
	v_exp_f32_e32 v48, v48
	v_exp_f32_e32 v49, v49
	v_add_f32_e32 v48, 1.0, v48
	v_add_f32_e32 v49, 1.0, v49
	v_rcp_f32_e32 v48, v48
	v_rcp_f32_e32 v49, v49
	s_nop 0
; __device__ __forceinline__ unsigned pk2(float lo, float hi) { f32x2 v = {lo, hi}; bf16x2_t b = __builtin_convertvector(v, bf16x2_t); return __builtin_bit_cast(unsigned, b); }
; __device__ __forceinline__ float sigmoidf_(float x) { return __builtin_amdgcn_rcpf(1.0f + __builtin_amdgcn_exp2f(-x * LOG2E)); }
;     __device__ __forceinline__ void operator()(const f32x4 (&acc)[2][2][4][2], const Unit& u, int wr, int wc, int fr, int fq, LAS unsigned char* lds, int tid) const {
;     ...
;         for (int ai = 0; ai < 2; ++ai)
; #pragma unroll
;             for (int m = 0; m < 4; ++m) { const size_t row = (size_t)(row0 + ai * HALF + m * 16); const float rs = rsv[ai][m]; gbf16* rowp = O + row * FF + col0;
;                 float h[8];
; #pragma unroll
;                 for (int n = 0; n < 2; ++n)
; #pragma unroll
;                     for (int e = 0; e < 4; ++e) { const float g = acc[ai][0][m][n][e] * rs, uu = acc[ai][1][m][n][e] * rs; h[n * 4 + e] = g * sigmoidf_(g) * uu; }
;                 u32x4 w; w.x = pk2(h[0], h[1]); w.y = pk2(h[2], h[3]); w.z = pk2(h[4], h[5]); w.w = pk2(h[6], h[7]);
;                 *(gu32x4*)rowp = w; }
	v_pk_mul_f32 v[46:47], v[46:47], v[48:49]
	s_nop 0
	v_pk_mul_f32 v[44:45], v[44:45], v[46:47]
	v_mul_f32_e32 v46, 0xbfb8aa3b, v38
	v_mul_f32_e32 v47, 0xbfb8aa3b, v39
	v_exp_f32_e32 v46, v46
	v_exp_f32_e32 v47, v47
	v_add_f32_e32 v46, 1.0, v46
	v_add_f32_e32 v47, 1.0, v47
	v_rcp_f32_e32 v46, v46
	v_rcp_f32_e32 v47, v47
	s_nop 0
	v_pk_mul_f32 v[38:39], v[38:39], v[46:47]
	s_nop 0
	v_pk_mul_f32 v[38:39], v[34:35], v[38:39]
	v_pk_mul_f32 v[34:35], v[40:41], v[150:151] op_sel_hi:[1,0]
	v_lshl_add_u64 v[46:47], v[50:51], 0, v[114:115]
	v_mul_f32_e32 v40, 0xbfb8aa3b, v34
	v_mul_f32_e32 v41, 0xbfb8aa3b, v35
	v_exp_f32_e32 v40, v40
	v_exp_f32_e32 v41, v41
	v_add_f32_e32 v40, 1.0, v40
	v_add_f32_e32 v41, 1.0, v41
	v_rcp_f32_e32 v40, v40
	v_rcp_f32_e32 v41, v41
	s_nop 0
	v_pk_mul_f32 v[34:35], v[34:35], v[40:41]
	s_nop 0
	v_pk_mul_f32 v[40:41], v[36:37], v[34:35]
	v_cvt_pk_bf16_f32 v34, v42, v43
	v_cvt_pk_bf16_f32 v35, v44, v45
	v_cvt_pk_bf16_f32 v36, v38, v39
	v_cvt_pk_bf16_f32 v37, v40, v41
	global_store_dwordx4 v[46:47], v[34:37], off
	s_nop 1
	v_mul_f32_e32 v36, 0xbfb8aa3b, v30
	v_mul_f32_e32 v37, 0xbfb8aa3b, v31
	v_exp_f32_e32 v36, v36
	v_exp_f32_e32 v37, v37
	v_mad_i64_i32 v[34:35], s[0:1], v146, s79, v[148:149]
	v_add_f32_e32 v36, 1.0, v36
	v_add_f32_e32 v37, 1.0, v37
	v_rcp_f32_e32 v36, v36
	v_rcp_f32_e32 v37, v37
	s_nop 0
	v_pk_mul_f32 v[30:31], v[30:31], v[36:37]
	s_nop 0
	v_pk_mul_f32 v[26:27], v[26:27], v[30:31]
	v_pk_mul_f32 v[30:31], v[32:33], v[144:145] op_sel_hi:[1,0]
	s_nop 0
	v_mul_f32_e32 v32, 0xbfb8aa3b, v30
	v_mul_f32_e32 v33, 0xbfb8aa3b, v31
	v_exp_f32_e32 v32, v32
	v_exp_f32_e32 v33, v33
	v_add_f32_e32 v32, 1.0, v32
	v_add_f32_e32 v33, 1.0, v33
	v_rcp_f32_e32 v32, v32
	v_rcp_f32_e32 v33, v33
	s_nop 0
	v_pk_mul_f32 v[30:31], v[30:31], v[32:33]
	s_nop 0
	v_pk_mul_f32 v[28:29], v[28:29], v[30:31]
	v_mul_f32_e32 v30, 0xbfb8aa3b, v22
	v_mul_f32_e32 v31, 0xbfb8aa3b, v23
	v_exp_f32_e32 v30, v30
	v_exp_f32_e32 v31, v31
	v_add_f32_e32 v30, 1.0, v30
	v_add_f32_e32 v31, 1.0, v31
	v_rcp_f32_e32 v30, v30
	v_rcp_f32_e32 v31, v31
	s_nop 0
	v_pk_mul_f32 v[22:23], v[22:23], v[30:31]
	s_nop 0
	v_pk_mul_f32 v[22:23], v[18:19], v[22:23]
	v_pk_mul_f32 v[18:19], v[24:25], v[144:145] op_sel_hi:[1,0]
	v_lshl_add_u64 v[30:31], v[34:35], 0, v[114:115]
	v_mul_f32_e32 v24, 0xbfb8aa3b, v18
	v_mul_f32_e32 v25, 0xbfb8aa3b, v19
	v_exp_f32_e32 v24, v24
	v_exp_f32_e32 v25, v25
	v_add_f32_e32 v24, 1.0, v24
	v_add_f32_e32 v25, 1.0, v25
	v_rcp_f32_e32 v24, v24
	v_rcp_f32_e32 v25, v25
	s_nop 0
	v_pk_mul_f32 v[18:19], v[18:19], v[24:25]
	s_nop 0
	v_pk_mul_f32 v[24:25], v[20:21], v[18:19]
	v_cvt_pk_bf16_f32 v18, v26, v27
	v_cvt_pk_bf16_f32 v19, v28, v29
	v_cvt_pk_bf16_f32 v20, v22, v23
	v_cvt_pk_bf16_f32 v21, v24, v25
	global_store_dwordx4 v[30:31], v[18:21], off
	s_nop 1
	v_mul_f32_e32 v20, 0xbfb8aa3b, v14
	v_mul_f32_e32 v21, 0xbfb8aa3b, v15
	v_exp_f32_e32 v20, v20
	v_exp_f32_e32 v21, v21
	v_mad_i64_i32 v[18:19], s[0:1], v140, s79, v[148:149]
	v_add_f32_e32 v20, 1.0, v20
	v_add_f32_e32 v21, 1.0, v21
	v_rcp_f32_e32 v20, v20
	v_rcp_f32_e32 v21, v21
	s_mov_b64 s[0:1], -1
	v_pk_mul_f32 v[14:15], v[14:15], v[20:21]
	s_nop 0
	v_pk_mul_f32 v[10:11], v[10:11], v[14:15]
	v_pk_mul_f32 v[14:15], v[16:17], v[142:143] op_sel_hi:[1,0]
	s_nop 0
	v_mul_f32_e32 v16, 0xbfb8aa3b, v14
	v_mul_f32_e32 v17, 0xbfb8aa3b, v15
	v_exp_f32_e32 v16, v16
	v_exp_f32_e32 v17, v17
	v_add_f32_e32 v16, 1.0, v16
	v_add_f32_e32 v17, 1.0, v17
	v_rcp_f32_e32 v16, v16
	v_rcp_f32_e32 v17, v17
	s_nop 0
	v_pk_mul_f32 v[14:15], v[14:15], v[16:17]
	s_nop 0
	v_pk_mul_f32 v[12:13], v[12:13], v[14:15]
	v_mul_f32_e32 v14, 0xbfb8aa3b, v6
	v_mul_f32_e32 v15, 0xbfb8aa3b, v7
	v_exp_f32_e32 v14, v14
	v_exp_f32_e32 v15, v15
	v_add_f32_e32 v14, 1.0, v14
	v_add_f32_e32 v15, 1.0, v15
	v_rcp_f32_e32 v14, v14
	v_rcp_f32_e32 v15, v15
	s_nop 0
	v_pk_mul_f32 v[6:7], v[6:7], v[14:15]
	s_nop 0
	v_pk_mul_f32 v[6:7], v[2:3], v[6:7]
	v_pk_mul_f32 v[2:3], v[8:9], v[142:143] op_sel_hi:[1,0]
	v_lshl_add_u64 v[14:15], v[18:19], 0, v[114:115]
	v_mul_f32_e32 v8, 0xbfb8aa3b, v2
	v_mul_f32_e32 v9, 0xbfb8aa3b, v3
	v_exp_f32_e32 v8, v8
	v_exp_f32_e32 v9, v9
	v_add_f32_e32 v8, 1.0, v8
	v_add_f32_e32 v9, 1.0, v9
	v_rcp_f32_e32 v8, v8
	v_rcp_f32_e32 v9, v9
	s_nop 0
	v_pk_mul_f32 v[2:3], v[2:3], v[8:9]
	s_nop 0
	v_pk_mul_f32 v[8:9], v[4:5], v[2:3]
	v_cvt_pk_bf16_f32 v2, v10, v11
	v_cvt_pk_bf16_f32 v3, v12, v13
	v_cvt_pk_bf16_f32 v4, v6, v7
	v_cvt_pk_bf16_f32 v5, v8, v9
	global_store_dwordx4 v[14:15], v[2:5], off
	s_cbranch_vccnz .LBB0_365
	s_andn2_b64 vcc, exec, s[4:5]
	s_cbranch_vccnz .LBB0_364
	s_barrier
	s_branch .LBB0_364

;     __device__ bool next(int i, Unit& u) const { if (!b.next(i / 3, u)) return false; u.pz = i % 3; return true; }
; #define PG8_STAGE(bufoff, gbase, voff) do { _Pragma("unroll") for (int _i = 0; _i < 2; ++_i) \
;         __builtin_amdgcn_global_load_lds((const gunsigned*)((const gchar*)(gbase) + (voff)[_i]), (LAS unsigned*)(lds + (bufoff) + ldsw + _i * 8192), 16, 0, 0); } while (0)
; #define PG8_WAIT_V(n) asm volatile("s_waitcnt vmcnt(" #n ")" ::: "memory")
; template <class Epi, class Sched>
; __device__ __forceinline__ void gemm_phase(LAS unsigned char* lds, const int tid, const Gemm g, const Sched& S, const Epi& E) {
;     const int wid = __builtin_amdgcn_readfirstlane(tid >> 6), lane = tid & 63, wr = wid >> 2, wc = wid & 3, fr = lane & 15, fq = lane >> 4;
;     const int K = g.K, nt = K / BK;
;     unsigned voffA[2], voffB[2];
; #pragma unroll
;     for (int i = 0; i < 2; ++i) { int R, C; stage_rc(tid * 16 + i * 8192, R, C); const int Rb = Epi::PERM ? ((R & ~31) + perm32(R & 31)) : R;
;         voffA[i] = (unsigned)(R * K + C) * 2u; voffB[i] = (unsigned)(Rb * K + C) * 2u; }
;     const size_t kstep = (size_t)(BK * 2);
;     const size_t hstep = (size_t)HALF * K * 2;
;     const size_t tstep = 2 * hstep;
;     const unsigned ldsw = (unsigned)wid * 1024u;
;     const int aoff = lds_byte(wr * 64 + fr, fq * 8), boff = lds_byte(wc * 32 + fr, fq * 8);
;     ...
;     Unit cur, nxt; int ui = 0;
;     if (!S.next(0, cur)) return;
;     f32x4 acc[2][2][4][2];
; #pragma unroll
;     for (int a = 0; a < 2; ++a)
; #pragma unroll
;         for (int b = 0; b < 2; ++b)
; #pragma unroll
;             for (int m = 0; m < 4; ++m)
; #pragma unroll
;                 for (int n = 0; n < 2; ++n) acc[a][b][m][n] = (f32x4){0.f, 0.f, 0.f, 0.f};
;     bf16x8 At[4][2], B0[2][2], B1[2][2];
;     const gchar* cA = (const gchar*)g.A + (size_t)cur.pm * tstep + (size_t)cur.pz * g.zA; const gchar* cB = (const gchar*)g.Bt + (size_t)cur.pn * tstep + (size_t)cur.pz * g.zB;
;     PG8_STAGE(PG8_SB(0, 0), cB, voffB); PG8_STAGE(PG8_SB(0, 1), cB + hstep, voffB); PG8_STAGE(PG8_SA(0, 0), cA, voffA); PG8_STAGE(PG8_SA(0, 1), cA + hstep, voffA);
;     if (wr == 1) PG8_BAR;
;     PG8_WAIT_V(2); PG8_BAR;
;     PG8_STAGE(PG8_SB(1, 0), cB + kstep, voffB); PG8_STAGE(PG8_SA(1, 0), cA + kstep, voffA); PG8_STAGE(PG8_SB(1, 1), cB + hstep + kstep, voffB);
;     PG8_WAIT_V(6); PG8_BAR;
.LBB0_553:
	v_mov_b32_e32 v242, -1
	v_lshrrev_b32_e32 v17, 1, v240
	v_and_b32_e32 v17, 24, v17
	v_and_b32_e32 v16, 15, v240
	v_lshlrev_b32_e32 v18, 1, v17
	v_lshl_or_b32 v163, s5, 6, v16
	v_lshl_or_b32 v16, v16, 6, v18
	v_lshlrev_b32_e32 v18, 2, v240
	s_sext_i32_i16 s31, s2
	s_lshl_b32 s2, s5, 13
	v_and_b32_e32 v18, 32, v18
	v_bitop3_b32 v19, v16, s2, v18 bitop3:0xde
	s_lshl_b32 s2, s4, 5
	s_and_b32 s2, s2, 0x60
	s_add_i32 m0, s34, 0x18000
	v_lshl_add_u64 v[8:9], v[8:9], 0, s[68:69]
	s_lshl_b32 s4, s2, 7
	s_waitcnt vmcnt(2)
	s_barrier
	global_load_lds_dwordx4 v[8:9], off
	v_lshl_add_u64 v[6:7], v[6:7], 0, s[68:69]
	s_add_i32 m0, s34, 0x1a000
	s_add_i32 s38, s34, 0x8000
	s_add_i32 s39, s34, 0xa000
	v_bitop3_b32 v165, s4, v16, v18 bitop3:0xf6
	global_load_lds_dwordx4 v[6:7], off
	v_lshl_add_u64 v[2:3], v[2:3], 0, s[68:69]
	s_mov_b32 m0, s38
	s_add_u32 s4, s20, 0x40080
	global_load_lds_dwordx4 v[2:3], off
	v_lshl_add_u64 v[2:3], v[4:5], 0, s[68:69]
	s_mov_b32 m0, s39
	s_addc_u32 s5, s21, 0
	global_load_lds_dwordx4 v[2:3], off
	s_add_i32 m0, s34, 0x1c000
	v_lshl_add_u64 v[2:3], s[4:5], 0, v[0:1]
	global_load_lds_dwordx4 v[2:3], off
	v_lshl_add_u64 v[2:3], s[4:5], 0, v[134:135]
	s_add_i32 m0, s34, 0x1e000
	s_cmpk_lt_u32 s3, 0x100
	global_load_lds_dwordx4 v[2:3], off
	v_lshlrev_b32_e32 v2, 14, v10
	v_and_b32_e32 v2, 0xffff8000, v2
	v_lshl_add_u32 v2, v11, 11, v2
	v_and_b32_e32 v3, 1, v10
	v_lshl_or_b32 v2, v3, 6, v2
	v_lshl_add_u32 v140, v12, 1, v2
	v_lshlrev_b32_e32 v2, 14, v14
	v_and_b32_e32 v2, 0xffff8000, v2
	s_waitcnt vmcnt(6)
	v_lshl_add_u32 v2, v13, 11, v2
	v_and_b32_e32 v3, 1, v14
	v_lshl_or_b32 v2, v3, 6, v2
	s_cselect_b64 s[4:5], -1, 0
	v_or_b32_e32 v167, s2, v17
	v_mov_b32_e32 v141, v1
	v_lshl_add_u32 v142, v15, 1, v2
	v_mov_b32_e32 v143, v1
	s_mov_b32 s40, 0
	v_add_u32_e32 v169, 0, v19
	s_barrier
	s_branch .LBB0_556

; #define LAS __attribute__((address_space(3)))
; __device__ __forceinline__ unsigned pk2(float lo, float hi) { f32x2 v = {lo, hi}; bf16x2_t b = __builtin_convertvector(v, bf16x2_t); return __builtin_bit_cast(unsigned, b); }
;     __device__ __forceinline__ void operator()(const f32x4 (&acc)[2][2][4][2], const Unit& u, int wr, int wc, int fr, int fq, LAS unsigned char* lds, int tid) const {
;         const int row0 = u.pm * BM + wr * 64 + fr, col0 = u.pn * BM + wc * 32 + 8 * fq;
;         const float tsc = !qscale ? 1.0f : (u.pn == 3 || u.pn == 4) ? 0.125f * LOG2E : (u.pn == 6 || u.pn == 7) ? 0.08838834764831845f * LOG2E : 1.0f;
;         float rsv[2][4];
;         { f32x4 pv_[2][4];
; #pragma unroll
;           for (int ai = 0; ai < 2; ++ai)
; #pragma unroll
;               for (int m = 0; m < 4; ++m) pv_[ai][m] = *(const gf32x4*)(ssq + (size_t)(row0 + ai * HALF + m * 16) * 4);
;           asm volatile("" ::: "memory");
; #pragma unroll
;           for (int ai = 0; ai < 2; ++ai)
; #pragma unroll
;               for (int m = 0; m < 4; ++m) { const f32x4 p = pv_[ai][m]; rsv[ai][m] = __builtin_amdgcn_rsqf(((p.x + p.y) + (p.z + p.w)) * (1.0f / DM) + EPS) * tsc; } }
; #pragma unroll
;         for (int ai = 0; ai < 2; ++ai)
; #pragma unroll
;             for (int m = 0; m < 4; ++m) { const size_t row = (size_t)(row0 + ai * HALF + m * 16); const float rs = rsv[ai][m]; gbf16* rowp = O + row * ldc + col0;
; #pragma unroll
;                 for (int bj = 0; bj < 2; ++bj) { const f32x4 v0 = acc[ai][bj][m][0] * rs, v1 = acc[ai][bj][m][1] * rs;
;                     u32x4 w; w.x = pk2(v0[0], v0[1]); w.y = pk2(v0[2], v0[3]); w.z = pk2(v1[0], v1[1]); w.w = pk2(v1[2], v1[3]);
;                     *(gu32x4*)(rowp + bj * HALF) = w; } }
.LBB0_568:
	v_lshl_add_u32 v160, s58, 8, v163
	v_or_b32_e32 v156, 16, v160
	v_or_b32_e32 v154, 32, v160
	v_or_b32_e32 v152, 48, v160
	v_add_u32_e32 v150, 0x80, v160
	v_add_u32_e32 v148, 0x90, v160
	v_add_u32_e32 v146, 0xa0, v160
	v_add_u32_e32 v144, 0xb0, v160
	v_lshl_or_b32 v158, s31, 8, v167
	v_readfirstlane_b32 vcc_lo, v242
	s_cmp_eq_u32 s58, vcc_lo
	s_cbranch_scc1 .Lk3_rs_hit
	v_mov_b32_e32 v242, s58
	v_ashrrev_i32_e32 v161, 31, v160
	v_lshl_add_u64 v[130:131], v[160:161], 4, s[70:71]
	global_load_dwordx4 v[170:173], v[130:131], off
	v_ashrrev_i32_e32 v157, 31, v156
	v_lshl_add_u64 v[130:131], v[156:157], 4, s[70:71]
	global_load_dwordx4 v[176:179], v[130:131], off
	v_ashrrev_i32_e32 v155, 31, v154
	v_lshl_add_u64 v[130:131], v[154:155], 4, s[70:71]
	global_load_dwordx4 v[180:183], v[130:131], off
	v_ashrrev_i32_e32 v153, 31, v152
	v_lshl_add_u64 v[130:131], v[152:153], 4, s[70:71]
	global_load_dwordx4 v[184:187], v[130:131], off
	v_ashrrev_i32_e32 v151, 31, v150
	v_lshl_add_u64 v[130:131], v[150:151], 4, s[70:71]
	global_load_dwordx4 v[188:191], v[130:131], off
	v_ashrrev_i32_e32 v149, 31, v148
	v_lshl_add_u64 v[130:131], v[148:149], 4, s[70:71]
	global_load_dwordx4 v[192:195], v[130:131], off
	v_ashrrev_i32_e32 v147, 31, v146
	v_lshl_add_u64 v[130:131], v[146:147], 4, s[70:71]
	global_load_dwordx4 v[204:207], v[130:131], off
	v_ashrrev_i32_e32 v145, 31, v144
	v_lshl_add_u64 v[130:131], v[144:145], 4, s[70:71]
	global_load_dwordx4 v[130:133], v[130:131], off
	s_waitcnt vmcnt(0)
	v_add_f32_e32 v170, v170, v171
	v_add_f32_e32 v172, v172, v173
	v_add_f32_e32 v170, v170, v172
	v_fmamk_f32 v170, v170, 0x3a800000, v235
	v_rsq_f32_e32 v226, v170
	v_add_f32_e32 v176, v176, v177
	v_add_f32_e32 v178, v178, v179
	v_add_f32_e32 v176, v176, v178
	v_fmamk_f32 v176, v176, 0x3a800000, v235
	v_rsq_f32_e32 v236, v176
	v_add_f32_e32 v180, v180, v181
	v_add_f32_e32 v182, v182, v183
	v_add_f32_e32 v180, v180, v182
	v_fmamk_f32 v180, v180, 0x3a800000, v235
	v_rsq_f32_e32 v237, v180
	v_add_f32_e32 v184, v184, v185
	v_add_f32_e32 v186, v186, v187
	v_add_f32_e32 v184, v184, v186
	v_fmamk_f32 v184, v184, 0x3a800000, v235
	v_rsq_f32_e32 v244, v184
	v_add_f32_e32 v188, v188, v189
	v_add_f32_e32 v190, v190, v191
	v_add_f32_e32 v188, v188, v190
	v_fmamk_f32 v188, v188, 0x3a800000, v235
	v_rsq_f32_e32 v245, v188
	v_add_f32_e32 v192, v192, v193
	v_add_f32_e32 v194, v194, v195
	v_add_f32_e32 v192, v192, v194
	v_fmamk_f32 v192, v192, 0x3a800000, v235
	v_rsq_f32_e32 v246, v192
	v_add_f32_e32 v204, v204, v205
	v_add_f32_e32 v206, v206, v207
	v_add_f32_e32 v204, v204, v206
	v_fmamk_f32 v204, v204, 0x3a800000, v235
	v_rsq_f32_e32 v247, v204
	v_add_f32_e32 v130, v130, v131
	v_add_f32_e32 v132, v132, v133
	v_add_f32_e32 v130, v130, v132
	v_fmamk_f32 v130, v130, 0x3a800000, v235
	v_rsq_f32_e32 v248, v130
.Lk3_rs_hit:
	s_andn2_b64 vcc, exec, s[2:3]
	v_mul_f32_e32 v174, v159, v226
	v_mul_f32_e32 v172, v159, v236
	v_mul_f32_e32 v170, v159, v237
	v_mul_f32_e32 v168, v159, v244
	v_mul_f32_e32 v166, v159, v245
	v_mul_f32_e32 v164, v159, v246
	v_mul_f32_e32 v162, v159, v247
	v_mul_f32_e32 v130, v159, v248
	v_mov_b64_e32 v[132:133], s[96:97]
	v_mad_i64_i32 v[160:161], s[20:21], v160, s33, v[132:133]
	v_ashrrev_i32_e32 v159, 31, v158
	v_lshlrev_b64 v[158:159], 1, v[158:159]
	v_pk_mul_f32 v[128:129], v[128:129], v[174:175] op_sel_hi:[1,0]
	v_pk_mul_f32 v[126:127], v[126:127], v[174:175] op_sel_hi:[1,0]
	v_pk_mul_f32 v[176:177], v[124:125], v[174:175] op_sel_hi:[1,0]
	v_pk_mul_f32 v[124:125], v[122:123], v[174:175] op_sel_hi:[1,0]
	v_lshl_add_u64 v[160:161], v[160:161], 0, v[158:159]
	v_cvt_pk_bf16_f32 v122, v126, v127
	v_cvt_pk_bf16_f32 v123, v128, v129
	v_cvt_pk_bf16_f32 v124, v124, v125
	v_cvt_pk_bf16_f32 v125, v176, v177
	global_store_dwordx4 v[160:161], v[122:125], off
	v_pk_mul_f32 v[116:117], v[116:117], v[174:175] op_sel_hi:[1,0]
	v_pk_mul_f32 v[114:115], v[114:115], v[174:175] op_sel_hi:[1,0]
	v_pk_mul_f32 v[122:123], v[108:109], v[174:175] op_sel_hi:[1,0]
	v_pk_mul_f32 v[108:109], v[106:107], v[174:175] op_sel_hi:[1,0]
	v_cvt_pk_bf16_f32 v106, v114, v115
	v_cvt_pk_bf16_f32 v107, v116, v117
	v_cvt_pk_bf16_f32 v108, v108, v109
	v_cvt_pk_bf16_f32 v109, v122, v123
	global_store_dwordx4 v[160:161], v[106:109], off offset:256
	v_pk_mul_f32 v[112:113], v[112:113], v[172:173] op_sel_hi:[1,0]
	v_pk_mul_f32 v[110:111], v[110:111], v[172:173] op_sel_hi:[1,0]
	v_mad_i64_i32 v[106:107], s[20:21], v156, s33, v[132:133]
	v_lshl_add_u64 v[114:115], v[106:107], 0, v[158:159]
	v_pk_mul_f32 v[108:109], v[120:121], v[172:173] op_sel_hi:[1,0]
	v_pk_mul_f32 v[106:107], v[118:119], v[172:173] op_sel_hi:[1,0]
	v_pk_mul_f32 v[100:101], v[100:101], v[172:173] op_sel_hi:[1,0]
	v_cvt_pk_bf16_f32 v106, v106, v107
	v_cvt_pk_bf16_f32 v107, v108, v109
	v_cvt_pk_bf16_f32 v108, v110, v111
	v_cvt_pk_bf16_f32 v109, v112, v113
	global_store_dwordx4 v[114:115], v[106:109], off
	v_pk_mul_f32 v[98:99], v[98:99], v[172:173] op_sel_hi:[1,0]
	v_pk_mul_f32 v[96:97], v[96:97], v[170:171] op_sel_hi:[1,0]
	v_pk_mul_f32 v[106:107], v[92:93], v[172:173] op_sel_hi:[1,0]
	v_pk_mul_f32 v[92:93], v[90:91], v[172:173] op_sel_hi:[1,0]
	v_cvt_pk_bf16_f32 v90, v98, v99
	v_cvt_pk_bf16_f32 v91, v100, v101
	v_cvt_pk_bf16_f32 v92, v92, v93
	v_cvt_pk_bf16_f32 v93, v106, v107
	global_store_dwordx4 v[114:115], v[90:93], off offset:256
	v_pk_mul_f32 v[94:95], v[94:95], v[170:171] op_sel_hi:[1,0]
	v_pk_mul_f32 v[84:85], v[84:85], v[170:171] op_sel_hi:[1,0]
	v_mad_i64_i32 v[90:91], s[20:21], v154, s33, v[132:133]
	v_lshl_add_u64 v[98:99], v[90:91], 0, v[158:159]
; __device__ __forceinline__ unsigned pk2(float lo, float hi) { f32x2 v = {lo, hi}; bf16x2_t b = __builtin_convertvector(v, bf16x2_t); return __builtin_bit_cast(unsigned, b); }
;     __device__ __forceinline__ void operator()(const f32x4 (&acc)[2][2][4][2], const Unit& u, int wr, int wc, int fr, int fq, LAS unsigned char* lds, int tid) const {
;     ...
; #pragma unroll
;         for (int ai = 0; ai < 2; ++ai)
; #pragma unroll
;             for (int m = 0; m < 4; ++m) { const size_t row = (size_t)(row0 + ai * HALF + m * 16); const float rs = rsv[ai][m]; gbf16* rowp = O + row * ldc + col0;
; #pragma unroll
;                 for (int bj = 0; bj < 2; ++bj) { const f32x4 v0 = acc[ai][bj][m][0] * rs, v1 = acc[ai][bj][m][1] * rs;
;                     u32x4 w; w.x = pk2(v0[0], v0[1]); w.y = pk2(v0[2], v0[3]); w.z = pk2(v1[0], v1[1]); w.w = pk2(v1[2], v1[3]);
;                     *(gu32x4*)(rowp + bj * HALF) = w; } }
	v_pk_mul_f32 v[92:93], v[104:105], v[170:171] op_sel_hi:[1,0]
	v_pk_mul_f32 v[90:91], v[102:103], v[170:171] op_sel_hi:[1,0]
	v_pk_mul_f32 v[82:83], v[82:83], v[170:171] op_sel_hi:[1,0]
	v_cvt_pk_bf16_f32 v90, v90, v91
	v_cvt_pk_bf16_f32 v91, v92, v93
	v_cvt_pk_bf16_f32 v92, v94, v95
	v_cvt_pk_bf16_f32 v93, v96, v97
	global_store_dwordx4 v[98:99], v[90:93], off
	v_pk_mul_f32 v[80:81], v[80:81], v[168:169] op_sel_hi:[1,0]
	v_pk_mul_f32 v[78:79], v[78:79], v[168:169] op_sel_hi:[1,0]
	v_pk_mul_f32 v[90:91], v[76:77], v[170:171] op_sel_hi:[1,0]
	v_pk_mul_f32 v[76:77], v[74:75], v[170:171] op_sel_hi:[1,0]
	v_cvt_pk_bf16_f32 v74, v82, v83
	v_cvt_pk_bf16_f32 v75, v84, v85
	v_cvt_pk_bf16_f32 v76, v76, v77
	v_cvt_pk_bf16_f32 v77, v90, v91
	global_store_dwordx4 v[98:99], v[74:77], off offset:256
	v_pk_mul_f32 v[72:73], v[72:73], v[168:169] op_sel_hi:[1,0]
	v_pk_mul_f32 v[70:71], v[70:71], v[168:169] op_sel_hi:[1,0]
	v_mad_i64_i32 v[74:75], s[20:21], v152, s33, v[132:133]
	v_lshl_add_u64 v[82:83], v[74:75], 0, v[158:159]
	v_pk_mul_f32 v[76:77], v[88:89], v[168:169] op_sel_hi:[1,0]
	v_pk_mul_f32 v[74:75], v[86:87], v[168:169] op_sel_hi:[1,0]
	v_pk_mul_f32 v[64:65], v[64:65], v[166:167] op_sel_hi:[1,0]
	v_cvt_pk_bf16_f32 v74, v74, v75
	v_cvt_pk_bf16_f32 v75, v76, v77
	v_cvt_pk_bf16_f32 v76, v78, v79
	v_cvt_pk_bf16_f32 v77, v80, v81
	global_store_dwordx4 v[82:83], v[74:77], off
	v_pk_mul_f32 v[62:63], v[62:63], v[166:167] op_sel_hi:[1,0]
	v_pk_mul_f32 v[52:53], v[52:53], v[166:167] op_sel_hi:[1,0]
	v_pk_mul_f32 v[74:75], v[68:69], v[168:169] op_sel_hi:[1,0]
	v_pk_mul_f32 v[68:69], v[66:67], v[168:169] op_sel_hi:[1,0]
	v_cvt_pk_bf16_f32 v66, v70, v71
	v_cvt_pk_bf16_f32 v67, v72, v73
	v_cvt_pk_bf16_f32 v68, v68, v69
	v_cvt_pk_bf16_f32 v69, v74, v75
	global_store_dwordx4 v[82:83], v[66:69], off offset:256
	v_pk_mul_f32 v[50:51], v[50:51], v[166:167] op_sel_hi:[1,0]
	v_pk_mul_f32 v[48:49], v[48:49], v[164:165] op_sel_hi:[1,0]
	v_mad_i64_i32 v[66:67], s[20:21], v150, s33, v[132:133]
	v_pk_mul_f32 v[68:69], v[60:61], v[166:167] op_sel_hi:[1,0]
	v_pk_mul_f32 v[60:61], v[58:59], v[166:167] op_sel_hi:[1,0]
	v_lshl_add_u64 v[66:67], v[66:67], 0, v[158:159]
	v_cvt_pk_bf16_f32 v58, v62, v63
	v_cvt_pk_bf16_f32 v59, v64, v65
	v_cvt_pk_bf16_f32 v60, v60, v61
	v_cvt_pk_bf16_f32 v61, v68, v69
	global_store_dwordx4 v[66:67], v[58:61], off
	v_pk_mul_f32 v[46:47], v[46:47], v[164:165] op_sel_hi:[1,0]
	v_pk_mul_f32 v[36:37], v[36:37], v[164:165] op_sel_hi:[1,0]
	v_pk_mul_f32 v[58:59], v[44:45], v[166:167] op_sel_hi:[1,0]
	v_pk_mul_f32 v[44:45], v[42:43], v[166:167] op_sel_hi:[1,0]
	v_cvt_pk_bf16_f32 v42, v50, v51
	v_cvt_pk_bf16_f32 v43, v52, v53
	v_cvt_pk_bf16_f32 v44, v44, v45
	v_cvt_pk_bf16_f32 v45, v58, v59
	global_store_dwordx4 v[66:67], v[42:45], off offset:256
	v_pk_mul_f32 v[34:35], v[34:35], v[164:165] op_sel_hi:[1,0]
	v_pk_mul_f32 v[32:33], v[32:33], v[162:163] op_sel_hi:[1,0]
	v_mad_i64_i32 v[42:43], s[20:21], v148, s33, v[132:133]
	v_lshl_add_u64 v[50:51], v[42:43], 0, v[158:159]
	v_pk_mul_f32 v[44:45], v[56:57], v[164:165] op_sel_hi:[1,0]
	v_pk_mul_f32 v[42:43], v[54:55], v[164:165] op_sel_hi:[1,0]
	v_pk_mul_f32 v[30:31], v[30:31], v[162:163] op_sel_hi:[1,0]
	v_cvt_pk_bf16_f32 v42, v42, v43
	v_cvt_pk_bf16_f32 v43, v44, v45
	v_cvt_pk_bf16_f32 v44, v46, v47
	v_cvt_pk_bf16_f32 v45, v48, v49
	global_store_dwordx4 v[50:51], v[42:45], off
	v_pk_mul_f32 v[20:21], v[20:21], v[162:163] op_sel_hi:[1,0]
	v_pk_mul_f32 v[18:19], v[18:19], v[162:163] op_sel_hi:[1,0]
	v_pk_mul_f32 v[42:43], v[28:29], v[164:165] op_sel_hi:[1,0]
	v_pk_mul_f32 v[28:29], v[26:27], v[164:165] op_sel_hi:[1,0]
	v_cvt_pk_bf16_f32 v26, v34, v35
	v_cvt_pk_bf16_f32 v27, v36, v37
	v_cvt_pk_bf16_f32 v28, v28, v29
	v_cvt_pk_bf16_f32 v29, v42, v43
	global_store_dwordx4 v[50:51], v[26:29], off offset:256
	v_pk_mul_f32 v[16:17], v[16:17], v[130:131] op_sel_hi:[1,0]
	v_pk_mul_f32 v[14:15], v[14:15], v[130:131] op_sel_hi:[1,0]
	v_mad_i64_i32 v[26:27], s[20:21], v146, s33, v[132:133]
	v_lshl_add_u64 v[34:35], v[26:27], 0, v[158:159]
	v_pk_mul_f32 v[28:29], v[40:41], v[162:163] op_sel_hi:[1,0]
	v_pk_mul_f32 v[26:27], v[38:39], v[162:163] op_sel_hi:[1,0]
	v_pk_mul_f32 v[8:9], v[8:9], v[130:131] op_sel_hi:[1,0]
	v_cvt_pk_bf16_f32 v26, v26, v27
	v_cvt_pk_bf16_f32 v27, v28, v29
	v_cvt_pk_bf16_f32 v28, v30, v31
	v_cvt_pk_bf16_f32 v29, v32, v33
	global_store_dwordx4 v[34:35], v[26:29], off
	v_pk_mul_f32 v[6:7], v[6:7], v[130:131] op_sel_hi:[1,0]
	s_nop 0
	v_pk_mul_f32 v[26:27], v[12:13], v[162:163] op_sel_hi:[1,0]
	v_pk_mul_f32 v[12:13], v[10:11], v[162:163] op_sel_hi:[1,0]
	v_cvt_pk_bf16_f32 v10, v18, v19
	v_cvt_pk_bf16_f32 v11, v20, v21
	v_cvt_pk_bf16_f32 v12, v12, v13
	v_cvt_pk_bf16_f32 v13, v26, v27
	global_store_dwordx4 v[34:35], v[10:13], off offset:256
	s_nop 1
	v_mad_i64_i32 v[10:11], s[20:21], v144, s33, v[132:133]
	v_lshl_add_u64 v[18:19], v[10:11], 0, v[158:159]
	v_pk_mul_f32 v[12:13], v[24:25], v[130:131] op_sel_hi:[1,0]
	v_pk_mul_f32 v[10:11], v[22:23], v[130:131] op_sel_hi:[1,0]
	s_mov_b64 s[20:21], -1
	v_cvt_pk_bf16_f32 v10, v10, v11
	v_cvt_pk_bf16_f32 v11, v12, v13
	v_cvt_pk_bf16_f32 v12, v14, v15
	v_cvt_pk_bf16_f32 v13, v16, v17
	global_store_dwordx4 v[18:19], v[10:13], off
	s_nop 1
	v_pk_mul_f32 v[10:11], v[4:5], v[130:131] op_sel_hi:[1,0]
	v_pk_mul_f32 v[4:5], v[2:3], v[130:131] op_sel_hi:[1,0]
	v_cvt_pk_bf16_f32 v2, v6, v7
	v_cvt_pk_bf16_f32 v3, v8, v9
	v_cvt_pk_bf16_f32 v4, v4, v5
	v_cvt_pk_bf16_f32 v5, v10, v11
	global_store_dwordx4 v[18:19], v[2:5], off offset:256
	s_cbranch_vccnz .LBB0_555
	s_andn2_b64 vcc, exec, s[0:1]
	s_cbranch_vccnz .LBB0_554
	s_barrier
	s_branch .LBB0_554
